# v19 + phase-1 cross-tile prefetch: next tile's first two K-steps of LDS-DMA stage loads issued at epilogue start
# speedup vs baseline: 1.0386x; 1.0037x over previous
.LBB0_204:
	s_mov_b64 s[98:99], -1
	s_add_u32 s0, s38, 0xc7b7200
	s_addc_u32 s1, s39, 0
	s_add_i32 s53, s49, 0xfffffc8c
	s_bitcmp1_b32 s49, 0
	v_writelane_b32 v255, s0, 28
	s_cselect_b64 s[94:95], -1, 0
	s_bitcmp1_b32 s35, 0
	v_writelane_b32 v255, s1, 29
	s_cselect_b64 s[0:1], -1, 0
	v_writelane_b32 v255, s0, 30
	s_mov_b32 s50, 0x3ffff0
	s_add_i32 s51, 16, 0x10000
	v_writelane_b32 v255, s1, 31
	s_mov_b32 s1, 0
	v_writelane_b32 v255, s0, 32
	s_add_i32 s52, 16, 0x14000
	v_mov_b32_e32 v197, 0
	v_writelane_b32 v255, s1, 33
	s_add_i32 s54, 16, 0x18000
	s_add_i32 s55, 16, 0x1c000
	s_mov_b64 s[74:75], 0x2bd1880
	s_mov_b64 s[24:25], 0x2200100
	s_mov_b64 s[26:27], 0x2b91900
	s_mov_b64 s[28:29], 0x2240100
	s_mov_b64 s[30:31], 0x2bd1900
	s_mov_b64 s[40:41], 0x2200180
	s_mov_b64 s[42:43], 0x2b91980
	s_mov_b64 s[44:45], 0x2240180
	s_mov_b64 s[58:59], 0x100
	s_mov_b32 s63, 0x800000
	s_mov_b64 s[64:65], 0x2351880
	s_mov_b64 s[66:67], 0x2311900
	s_mov_b64 s[68:69], 0x40100
	s_mov_b64 s[70:71], 0x2351900
	s_mov_b64 s[72:73], 0x180
	s_mov_b64 s[88:89], 0x2311980
	s_mov_b64 s[90:91], 0x40180
	s_movk_i32 s93, 0x300
	s_mov_b32 s57, 0x3f3504f3
	s_mov_b32 s97, 0x3ea7ba05
	v_mbcnt_hi_u32_b32 v195, -1, v193
	v_not_b32_e32 v215, 23
	v_not_b32_e32 v217, 29
	v_mov_b32_e32 v254, 0x1690000
	s_mov_b32 s96, 0x3f87dc22
	s_mov_b32 s62, 0x3fb5f0e3
	s_mov_b32 s48, 0xbe91a98e
	s_mov_b32 s92, 0x3e827906
	s_branch .LBB0_206

.LBB0_222:
	s_and_b64 vcc, exec, s[0:1]
	s_cbranch_vccz .LBB0_349
	s_mul_hi_i32 s0, s49, 0x4ec4ec4f
	s_lshr_b32 s1, s0, 31
	s_ashr_i32 s0, s0, 2
	s_add_i32 s10, s0, s1
	s_mul_i32 s0, s10, 13
	s_sub_i32 s0, s49, s0
	s_ashr_i32 s1, s0, 31
	s_lshl_b64 s[6:7], s[0:1], 19
	s_add_u32 s1, s60, s6
	s_addc_u32 vcc_lo, s61, s7
	s_add_u32 s4, s1, 0x2311800
	v_lshrrev_b32_e32 v8, 1, v244
	s_addc_u32 s5, vcc_lo, 0
	s_ashr_i32 s11, s10, 31
	v_or_b32_e32 v0, v8, v239
	v_ashrrev_i32_e32 v9, 7, v236
	s_lshl_b64 s[20:21], s[10:11], 19
	s_waitcnt vmcnt(0) lgkmcnt(0)
	v_lshl_or_b32 v130, v243, 10, v0
	v_and_or_b32 v1, v9, s50, v241
	s_add_u32 s18, s60, s20
	v_lshl_or_b32 v128, v1, 10, v0
	v_ashrrev_i32_e32 v131, 31, v130
	s_addc_u32 s19, s61, s21
	v_lshlrev_b64 v[10:11], 1, v[130:131]
	v_readfirstlane_b32 s17, v235
	v_ashrrev_i32_e32 v129, 31, v128
	v_add_u32_e32 v2, s51, v236
	s_waitcnt vmcnt(0)
	v_lshl_add_u64 v[0:1], s[18:19], 0, v[10:11]
	s_mov_b32 m0, s17
	v_lshlrev_b64 v[12:13], 1, v[128:129]
	v_readfirstlane_b32 s17, v2
	s_mov_b64 exec, s[98:99]
	global_load_lds_dwordx4 v[0:1], off
	s_mov_b64 exec, -1
	v_lshl_add_u64 v[4:5], s[18:19], 0, v[12:13]
	s_mov_b32 m0, s17
	v_readfirstlane_b32 s17, v237
	v_add_u32_e32 v141, 0x2000, v237
	s_mov_b64 exec, s[98:99]
	global_load_lds_dwordx4 v[4:5], off
	s_mov_b64 exec, -1
	v_lshl_add_u64 v[6:7], s[4:5], 0, v[10:11]
	s_mov_b32 m0, s17
	v_readfirstlane_b32 s17, v141
	s_add_u32 s46, s18, 0x40000
	s_mov_b64 exec, s[98:99]
	global_load_lds_dwordx4 v[6:7], off
	s_mov_b64 exec, -1
	v_lshl_add_u64 v[2:3], s[4:5], 0, v[12:13]
	s_mov_b32 m0, s17
	s_addc_u32 s47, s19, 0
	v_readfirstlane_b32 s17, v238
	s_mov_b64 exec, s[98:99]
	global_load_lds_dwordx4 v[2:3], off
	s_mov_b64 exec, -1
	v_lshl_add_u64 v[14:15], s[46:47], 0, v[10:11]
	s_mov_b32 m0, s17
	v_add_u32_e32 v16, s52, v236
	s_mov_b64 exec, s[98:99]
	global_load_lds_dwordx4 v[14:15], off
	s_mov_b64 exec, -1
	v_lshl_add_u64 v[14:15], s[46:47], 0, v[12:13]
	v_readfirstlane_b32 s17, v16
	s_add_u32 s46, s1, 0x2351800
	v_add_u32_e32 v142, 0x4000, v237
	s_mov_b32 m0, s17
	s_addc_u32 s47, vcc_lo, 0
	v_readfirstlane_b32 s1, v142
	v_add_u32_e32 v143, 0x6000, v237
	s_mov_b64 exec, s[98:99]
	global_load_lds_dwordx4 v[14:15], off
	s_mov_b64 exec, -1
	v_lshl_add_u64 v[10:11], s[46:47], 0, v[10:11]
	s_mov_b32 m0, s1
	v_readfirstlane_b32 s1, v143
	s_mov_b64 exec, s[98:99]
	global_load_lds_dwordx4 v[10:11], off
	s_mov_b64 exec, -1
	v_lshl_add_u64 v[10:11], s[46:47], 0, v[12:13]
	s_mov_b32 m0, s1
	s_mov_b32 s8, s10
	s_mov_b64 exec, s[98:99]
	global_load_lds_dwordx4 v[10:11], off
	s_mov_b64 exec, -1
	v_writelane_b32 v255, s8, 36
	v_cmp_eq_u32_e32 vcc, 1, v231
	s_nop 0
	v_writelane_b32 v255, s9, 37
	s_and_saveexec_b64 s[46:47], vcc
	s_cbranch_execz .LBB0_225
	s_barrier
.LBB0_225:
	s_or_b64 exec, exec, s[46:47]
	v_lshlrev_b32_e32 v10, 6, v230
	v_lshlrev_b32_e32 v12, 2, v230
	v_and_b32_e32 v11, 0x3c0, v10
	v_and_b32_e32 v12, 32, v12
	v_and_b32_e32 v236, 48, v230
	v_or_b32_e32 v14, v11, v236
	v_bitop3_b32 v11, v11, v12, v236 bitop3:0x36
	s_movk_i32 s1, 0x3000
	v_add_u32_e32 v145, s54, v242
	v_and_or_b32 v144, v10, s1, v11
	s_mov_b64 s[8:9], 0x80
	v_readfirstlane_b32 s1, v145
	v_add_u32_e32 v146, 0x2000, v145
	v_lshl_add_u64 v[0:1], v[0:1], 0, s[8:9]
	s_mov_b32 m0, s1
	v_readfirstlane_b32 s1, v146
	v_add_u32_e32 v147, 0x8000, v237
	s_waitcnt vmcnt(4)
	s_barrier
	s_mov_b64 exec, s[98:99]
	global_load_lds_dwordx4 v[0:1], off
	s_mov_b64 exec, -1
	v_lshl_add_u64 v[0:1], v[4:5], 0, s[8:9]
	s_mov_b32 m0, s1
	v_readfirstlane_b32 s1, v147
	v_add_u32_e32 v148, 0xa000, v237
	s_mov_b64 exec, s[98:99]
	global_load_lds_dwordx4 v[0:1], off
	s_mov_b64 exec, -1
	v_lshl_add_u64 v[0:1], v[6:7], 0, s[8:9]
	s_mov_b32 m0, s1
	v_readfirstlane_b32 s1, v148
	s_add_u32 s18, s18, 0x40080
	v_add_u32_e32 v149, s55, v242
	s_mov_b64 exec, s[98:99]
	global_load_lds_dwordx4 v[0:1], off
	s_mov_b64 exec, -1
	v_lshl_add_u64 v[0:1], v[2:3], 0, s[8:9]
	s_mov_b32 m0, s1
	s_addc_u32 s19, s19, 0
	v_readfirstlane_b32 s1, v149
	v_add_u32_e32 v150, 0x2000, v149
	s_mov_b64 exec, s[98:99]
	global_load_lds_dwordx4 v[0:1], off
	s_mov_b64 exec, -1
	v_lshl_add_u64 v[0:1], v[130:131], 1, s[18:19]
	s_mov_b32 m0, s1
	v_readfirstlane_b32 s1, v150
	s_mov_b64 exec, s[98:99]
	global_load_lds_dwordx4 v[0:1], off
	s_mov_b64 exec, -1
	v_lshl_add_u64 v[0:1], v[128:129], 1, s[18:19]
	s_mov_b32 m0, s1
	v_lshlrev_b32_e32 v2, 10, v241
	s_mov_b64 exec, s[98:99]
	global_load_lds_dwordx4 v[0:1], off
	s_mov_b64 exec, -1
	v_lshlrev_b32_e32 v0, 10, v9
	v_and_b32_e32 v0, 0xffffc000, v0
	v_lshlrev_b32_e32 v3, 10, v240
	v_or3_b32 v0, v8, v0, v2
	v_and_b32_e32 v3, 0xffffc000, v3
	v_add_u32_e32 v0, v0, v239
	v_or3_b32 v2, v8, v3, v2
	v_ashrrev_i32_e32 v1, 31, v0
	v_add_u32_e32 v2, v2, v239
	v_lshlrev_b32_e32 v13, 13, v231
	s_waitcnt vmcnt(6)
	v_lshlrev_b64 v[0:1], 1, v[0:1]
	v_ashrrev_i32_e32 v3, 31, v2
	v_bitop3_b32 v12, v14, v13, v12 bitop3:0xde
	v_lshl_add_u64 v[132:133], s[20:21], 0, v[0:1]
	v_lshlrev_b64 v[2:3], 1, v[2:3]
	v_lshl_add_u64 v[136:137], s[6:7], 0, v[0:1]
	v_mov_b32_e32 v0, 0
	v_lshl_add_u64 v[134:135], s[20:21], 0, v[2:3]
	v_lshl_add_u64 v[138:139], s[6:7], 0, v[2:3]
	s_mov_b32 s1, -2
	v_add_u32_e32 v140, 16, v12
	s_mov_b64 s[6:7], s[60:61]
	v_mov_b32_e32 v1, v0
	v_mov_b32_e32 v2, v0
	v_mov_b32_e32 v3, v0
	v_mov_b32_e32 v4, v0
	v_mov_b32_e32 v5, v0
	v_mov_b32_e32 v6, v0
	v_mov_b32_e32 v7, v0
	v_mov_b32_e32 v8, v0
	v_mov_b32_e32 v9, v0
	v_mov_b32_e32 v10, v0
	v_mov_b32_e32 v11, v0
	v_mov_b32_e32 v12, v0
	v_mov_b32_e32 v13, v0
	v_mov_b32_e32 v14, v0
	v_mov_b32_e32 v15, v0
	v_mov_b32_e32 v16, v0
	v_mov_b32_e32 v17, v0
	v_mov_b32_e32 v18, v0
	v_mov_b32_e32 v19, v0
	v_mov_b32_e32 v20, v0
	v_mov_b32_e32 v21, v0
	v_mov_b32_e32 v22, v0
	v_mov_b32_e32 v23, v0
	v_mov_b32_e32 v24, v0
	v_mov_b32_e32 v25, v0
	v_mov_b32_e32 v26, v0
	v_mov_b32_e32 v27, v0
	v_mov_b32_e32 v28, v0
	v_mov_b32_e32 v29, v0
	v_mov_b32_e32 v30, v0
	v_mov_b32_e32 v31, v0
	v_mov_b32_e32 v32, v0
	v_mov_b32_e32 v33, v0
	v_mov_b32_e32 v34, v0
	v_mov_b32_e32 v35, v0
	v_mov_b32_e32 v36, v0
	v_mov_b32_e32 v37, v0
	v_mov_b32_e32 v38, v0
	v_mov_b32_e32 v39, v0
	v_mov_b32_e32 v40, v0
	v_mov_b32_e32 v41, v0
	v_mov_b32_e32 v42, v0
	v_mov_b32_e32 v43, v0
	v_mov_b32_e32 v44, v0
	v_mov_b32_e32 v45, v0
	v_mov_b32_e32 v46, v0
	v_mov_b32_e32 v47, v0
	v_mov_b32_e32 v48, v0
	v_mov_b32_e32 v49, v0
	v_mov_b32_e32 v50, v0
	v_mov_b32_e32 v51, v0
	v_mov_b32_e32 v52, v0
	v_mov_b32_e32 v53, v0
	v_mov_b32_e32 v54, v0
	v_mov_b32_e32 v55, v0
	v_mov_b32_e32 v56, v0
	v_mov_b32_e32 v57, v0
	v_mov_b32_e32 v58, v0
	v_mov_b32_e32 v59, v0
	v_mov_b32_e32 v60, v0
	v_mov_b32_e32 v61, v0
	v_mov_b32_e32 v62, v0
	v_mov_b32_e32 v63, v0
	v_mov_b32_e32 v64, v0
	v_mov_b32_e32 v65, v0
	v_mov_b32_e32 v66, v0
	v_mov_b32_e32 v67, v0
	v_mov_b32_e32 v68, v0
	v_mov_b32_e32 v69, v0
	v_mov_b32_e32 v70, v0
	v_mov_b32_e32 v71, v0
	v_mov_b32_e32 v72, v0
	v_mov_b32_e32 v73, v0
	v_mov_b32_e32 v74, v0
	v_mov_b32_e32 v75, v0
	v_mov_b32_e32 v76, v0
	v_mov_b32_e32 v77, v0
	v_mov_b32_e32 v78, v0
	v_mov_b32_e32 v79, v0
	v_mov_b32_e32 v80, v0
	v_mov_b32_e32 v81, v0
	v_mov_b32_e32 v82, v0
	v_mov_b32_e32 v83, v0
	v_mov_b32_e32 v84, v0
	v_mov_b32_e32 v85, v0
	v_mov_b32_e32 v86, v0
	v_mov_b32_e32 v87, v0
	v_mov_b32_e32 v88, v0
	v_mov_b32_e32 v89, v0
	v_mov_b32_e32 v90, v0
	v_mov_b32_e32 v91, v0
	v_mov_b32_e32 v92, v0
	v_mov_b32_e32 v93, v0
	v_mov_b32_e32 v94, v0
	v_mov_b32_e32 v95, v0
	v_mov_b32_e32 v96, v0
	v_mov_b32_e32 v97, v0
	v_mov_b32_e32 v98, v0
	v_mov_b32_e32 v99, v0
	v_mov_b32_e32 v100, v0
	v_mov_b32_e32 v101, v0
	v_mov_b32_e32 v102, v0
	v_mov_b32_e32 v103, v0
	v_mov_b32_e32 v104, v0
	v_mov_b32_e32 v105, v0
	v_mov_b32_e32 v106, v0
	v_mov_b32_e32 v107, v0
	v_mov_b32_e32 v108, v0
	v_mov_b32_e32 v109, v0
	v_mov_b32_e32 v110, v0
	v_mov_b32_e32 v111, v0
	v_mov_b32_e32 v112, v0
	v_mov_b32_e32 v113, v0
	v_mov_b32_e32 v114, v0
	v_mov_b32_e32 v115, v0
	v_mov_b32_e32 v116, v0
	v_mov_b32_e32 v117, v0
	v_mov_b32_e32 v118, v0
	v_mov_b32_e32 v119, v0
	v_mov_b32_e32 v120, v0
	v_mov_b32_e32 v121, v0
	v_mov_b32_e32 v122, v0
	v_mov_b32_e32 v123, v0
	v_mov_b32_e32 v124, v0
	v_mov_b32_e32 v125, v0
	v_mov_b32_e32 v126, v0
	v_mov_b32_e32 v127, v0
	s_barrier

.LBB0_229:
	s_or_b64 exec, exec, s[4:5]
	s_mov_b64 s[98:99], -1
	s_add_i32 s4, s49, s35
	s_cmp_ge_i32 s4, s56
	s_cbranch_scc1 .Lpf1_skip
	s_cmpk_gt_i32 s4, 0x373
	s_cbranch_scc1 .Lpf1_skip
	s_mul_hi_i32 s5, s4, 0x4ec4ec4f
	s_lshr_b32 s6, s5, 31
	s_ashr_i32 s5, s5, 2
	s_add_i32 s5, s5, s6
	s_mul_i32 s6, s5, 13
	s_sub_i32 s6, s4, s6
	s_lshl_b32 s5, s5, 19
	s_lshl_b32 s6, s6, 19
	s_add_u32 s10, s38, s5
	s_addc_u32 s11, s39, 0
	s_add_u32 s12, s38, s6
	s_addc_u32 s13, s39, 0
	s_add_u32 s12, s12, 0x2311800
	s_addc_u32 s13, s13, 0
	s_add_u32 s14, s10, 0x40000
	s_addc_u32 s15, s11, 0
	s_add_u32 s16, s12, 0x40000
	s_addc_u32 s17, s13, 0
	v_lshrrev_b32_e32 v204, 3, v192
	v_and_b32_e32 v204, 0x30, v204
	v_bfe_u32 v205, v192, 2, 4
	v_or_b32_e32 v204, v204, v205
	v_lshrrev_b32_e32 v205, 1, v192
	v_and_b32_e32 v206, 3, v192
	v_lshlrev_b32_e32 v206, 3, v206
	v_and_b32_e32 v198, 16, v205
	v_xor_b32_e32 v206, v206, v198
	v_and_b32_e32 v205, 32, v205
	v_or_b32_e32 v206, v206, v205
	v_lshlrev_b32_e32 v206, 1, v206
	v_lshl_or_b32 v198, v204, 11, v206
	v_mov_b32_e32 v199, 0
	v_add_u32_e32 v200, 0x20000, v198
	v_mov_b32_e32 v201, 0
	v_readfirstlane_b32 s7, v192
	s_lshr_b32 s7, s7, 6
	s_lshl_b32 s7, s7, 10
	s_add_u32 s7, s7, 16
	s_add_u32 s22, s7, 0x10000
	v_lshl_add_u64 v[202:203], s[10:11], 0, v[198:199]
	s_mov_b32 m0, s22
	s_nop 0
	global_load_lds_dwordx4 v[202:203], off
	s_add_u32 s22, s7, 0x12000
	v_lshl_add_u64 v[202:203], s[10:11], 0, v[200:201]
	s_mov_b32 m0, s22
	s_nop 0
	global_load_lds_dwordx4 v[202:203], off
	s_add_u32 s22, s7, 0x0
	v_lshl_add_u64 v[202:203], s[12:13], 0, v[198:199]
	s_mov_b32 m0, s22
	s_nop 0
	global_load_lds_dwordx4 v[202:203], off
	s_add_u32 s22, s7, 0x2000
	v_lshl_add_u64 v[202:203], s[12:13], 0, v[200:201]
	s_mov_b32 m0, s22
	s_nop 0
	global_load_lds_dwordx4 v[202:203], off
	s_add_u32 s22, s7, 0x14000
	v_lshl_add_u64 v[202:203], s[14:15], 0, v[198:199]
	s_mov_b32 m0, s22
	s_nop 0
	global_load_lds_dwordx4 v[202:203], off
	s_add_u32 s22, s7, 0x16000
	v_lshl_add_u64 v[202:203], s[14:15], 0, v[200:201]
	s_mov_b32 m0, s22
	s_nop 0
	global_load_lds_dwordx4 v[202:203], off
	s_add_u32 s22, s7, 0x4000
	v_lshl_add_u64 v[202:203], s[16:17], 0, v[198:199]
	s_mov_b32 m0, s22
	s_nop 0
	global_load_lds_dwordx4 v[202:203], off
	s_add_u32 s22, s7, 0x6000
	v_lshl_add_u64 v[202:203], s[16:17], 0, v[200:201]
	s_mov_b32 m0, s22
	s_nop 0
	global_load_lds_dwordx4 v[202:203], off
	s_add_u32 s20, s10, 0x80
	s_addc_u32 s21, s11, 0
	s_add_u32 s22, s7, 0x18000
	v_lshl_add_u64 v[202:203], s[20:21], 0, v[198:199]
	s_mov_b32 m0, s22
	s_nop 0
	global_load_lds_dwordx4 v[202:203], off
	s_add_u32 s22, s7, 0x1a000
	v_lshl_add_u64 v[202:203], s[20:21], 0, v[200:201]
	s_mov_b32 m0, s22
	s_nop 0
	global_load_lds_dwordx4 v[202:203], off
	s_add_u32 s20, s12, 0x80
	s_addc_u32 s21, s13, 0
	s_add_u32 s22, s7, 0x8000
	v_lshl_add_u64 v[202:203], s[20:21], 0, v[198:199]
	s_mov_b32 m0, s22
	s_nop 0
	global_load_lds_dwordx4 v[202:203], off
	s_add_u32 s22, s7, 0xa000
	v_lshl_add_u64 v[202:203], s[20:21], 0, v[200:201]
	s_mov_b32 m0, s22
	s_nop 0
	global_load_lds_dwordx4 v[202:203], off
	s_add_u32 s20, s14, 0x80
	s_addc_u32 s21, s15, 0
	s_add_u32 s22, s7, 0x1c000
	v_lshl_add_u64 v[202:203], s[20:21], 0, v[198:199]
	s_mov_b32 m0, s22
	s_nop 0
	global_load_lds_dwordx4 v[202:203], off
	s_add_u32 s22, s7, 0x1e000
	v_lshl_add_u64 v[202:203], s[20:21], 0, v[200:201]
	s_mov_b32 m0, s22
	s_nop 0
	global_load_lds_dwordx4 v[202:203], off
	s_mov_b64 s[98:99], 0
.Lpf1_skip:
	v_readlane_b32 s4, v255, 36
	s_lshl_b32 s1, s4, 8
	v_lshl_or_b32 v128, v234, 5, s1
	v_and_b32_e32 v238, 63, v230
	v_or_b32_e32 v204, v128, v233
	v_readlane_b32 s5, v255, 37
	s_lshl_b32 s46, s0, 2
	s_cmpk_lt_i32 s49, 0x340
	s_cselect_b64 s[16:17], -1, 0
	s_cmpk_gt_i32 s49, 0x33f
	s_movk_i32 s0, 0x1f6f
	v_bitop3_b32 v235, v128, s0, v233 bitop3:0xc8
	s_cselect_b64 vcc, -1, 0
	s_add_u32 s0, s60, 0x2300000
	s_addc_u32 s1, s61, 0
	v_ashrrev_i32_e32 v205, 31, v204
	v_or_b32_e32 v202, 16, v204
	v_or_b32_e32 v200, 0x80, v204
	v_or_b32_e32 v198, 0x90, v204
	v_lshl_add_u64 v[206:207], v[204:205], 2, s[0:1]
	v_ashrrev_i32_e32 v203, 31, v202
	v_ashrrev_i32_e32 v201, 31, v200
	v_ashrrev_i32_e32 v199, 31, v198
	v_lshl_add_u64 v[208:209], v[202:203], 2, s[0:1]
	v_lshl_add_u64 v[210:211], v[200:201], 2, s[0:1]
	v_lshl_add_u64 v[212:213], v[198:199], 2, s[0:1]
	flat_load_dword v220, v[206:207]
	flat_load_dword v218, v[208:209]
	flat_load_dword v216, v[210:211]
	flat_load_dword v214, v[212:213]
	s_movk_i32 s0, 0x1f7f
	v_bitop3_b32 v234, v204, s0, 16 bitop3:0xc8
	s_movk_i32 s0, 0x1fef
	v_mov_b32_e32 v128, 0x80
	v_bitop3_b32 v233, v204, s0, v128 bitop3:0xc8
	s_movk_i32 s0, 0x1fff
	v_mov_b32_e32 v128, 0x90
	v_bitop3_b32 v223, v204, s0, v128 bitop3:0xc8
	s_add_u32 s0, s60, 0x2cc1800
	v_and_b32_e32 v237, 7, v230
	s_addc_u32 s1, s61, 0
	v_or_b32_e32 v129, 0x2000, v237
	v_add_u32_e32 v243, s46, v231
	v_writelane_b32 v255, s0, 38
	v_cndmask_b32_e32 v242, v235, v129, vcc
	v_cndmask_b32_e32 v241, v234, v129, vcc
	v_cndmask_b32_e32 v240, v233, v129, vcc
	v_cndmask_b32_e32 v239, v223, v129, vcc
	v_bfe_u32 v222, v230, 4, 2
	v_writelane_b32 v255, s1, 39
	v_cmp_lt_i32_e32 vcc, 5, v243
	s_and_saveexec_b64 s[0:1], vcc
	s_xor_b64 s[22:23], exec, s[0:1]
	s_cbranch_execz .LBB0_286
	v_cmp_lt_u32_e32 vcc, 11, v243
	s_and_saveexec_b64 s[0:1], vcc
	s_xor_b64 s[0:1], exec, s[0:1]
	s_cbranch_execz .LBB0_275
	v_writelane_b32 v255, s0, 40
	v_cmp_lt_u32_e32 vcc, 17, v243
	s_nop 0
	v_writelane_b32 v255, s1, 41
	s_and_saveexec_b64 s[0:1], vcc
	s_xor_b64 s[0:1], exec, s[0:1]
	s_cbranch_execz .LBB0_272
	v_writelane_b32 v255, s0, 42
	v_cmp_lt_u32_e32 vcc, 23, v243
	s_nop 0
	v_writelane_b32 v255, s1, 43
	s_and_saveexec_b64 s[0:1], vcc
	s_xor_b64 s[0:1], exec, s[0:1]
	s_cbranch_execz .LBB0_266
	v_writelane_b32 v255, s0, 44
	v_cmp_lt_u32_e32 vcc, 35, v243
	s_nop 0
	v_writelane_b32 v255, s1, 45
	s_and_saveexec_b64 s[0:1], vcc
	s_xor_b64 s[0:1], exec, s[0:1]
	s_cbranch_execz .LBB0_248
	v_cmp_lt_u32_e32 vcc, 41, v243
	s_and_saveexec_b64 s[4:5], vcc
	s_xor_b64 s[4:5], exec, s[4:5]
	s_cbranch_execz .LBB0_245
	v_cmp_lt_u32_e32 vcc, 45, v243
	s_and_saveexec_b64 s[6:7], vcc
	s_xor_b64 s[6:7], exec, s[6:7]
	s_cbranch_execz .LBB0_239
	v_cmp_gt_u32_e32 vcc, 50, v243
	s_and_saveexec_b64 s[20:21], vcc
	s_cbranch_execz .LBB0_238
	s_waitcnt vmcnt(0) lgkmcnt(0)
	v_pk_mul_f32 v[124:125], v[124:125], v[220:221] op_sel_hi:[1,0]
	v_pk_mul_f32 v[126:127], v[126:127], v[220:221] op_sel_hi:[1,0]
	v_mul_f32_e32 v132, 0xbfb8aa3b, v124
	v_mul_f32_e32 v133, 0xbfb8aa3b, v125
	v_exp_f32_e32 v132, v132
	v_exp_f32_e32 v133, v133
	v_lshlrev_b32_e32 v196, 7, v243
	v_lshl_add_u64 v[128:129], s[60:61], 0, v[196:197]
	v_add_f32_e32 v132, 1.0, v132
	v_add_f32_e32 v133, 1.0, v133
	v_rcp_f32_e32 v132, v132
	v_rcp_f32_e32 v133, v133
	v_and_b32_e32 v196, 24, v232
	v_lshl_add_u64 v[128:129], v[128:129], 0, v[196:197]
	s_mov_b64 s[8:9], 0x8f8c300
	v_pk_mul_f32 v[124:125], v[124:125], v[132:133]
	v_mul_f32_e32 v132, 0xbfb8aa3b, v126
	v_mul_f32_e32 v133, 0xbfb8aa3b, v127
	v_exp_f32_e32 v132, v132
	v_exp_f32_e32 v133, v133
	v_lshl_add_u64 v[128:129], v[128:129], 0, s[8:9]
	v_lshlrev_b64 v[130:131], 9, v[204:205]
	v_add_f32_e32 v132, 1.0, v132
	v_add_f32_e32 v133, 1.0, v133
	v_rcp_f32_e32 v132, v132
	v_rcp_f32_e32 v133, v133
	v_lshl_add_u64 v[130:131], v[128:129], 0, v[130:131]
	v_cvt_pk_bf16_f32 v124, v124, v125
	v_pk_mul_f32 v[120:121], v[120:121], v[220:221] op_sel_hi:[1,0]
	v_pk_mul_f32 v[126:127], v[126:127], v[132:133]
	v_pk_mul_f32 v[122:123], v[122:123], v[220:221] op_sel_hi:[1,0]
	v_cvt_pk_bf16_f32 v125, v126, v127
	flat_store_dwordx2 v[130:131], v[124:125]
	v_mul_f32_e32 v124, 0xbfb8aa3b, v120
	v_mul_f32_e32 v125, 0xbfb8aa3b, v121
	v_exp_f32_e32 v124, v124
	v_exp_f32_e32 v125, v125
	v_pk_mul_f32 v[116:117], v[116:117], v[220:221] op_sel_hi:[1,0]
	v_pk_mul_f32 v[118:119], v[118:119], v[220:221] op_sel_hi:[1,0]
	v_add_f32_e32 v124, 1.0, v124
	v_add_f32_e32 v125, 1.0, v125
	v_rcp_f32_e32 v124, v124
	v_rcp_f32_e32 v125, v125
	v_pk_mul_f32 v[112:113], v[112:113], v[220:221] op_sel_hi:[1,0]
	v_pk_mul_f32 v[114:115], v[114:115], v[220:221] op_sel_hi:[1,0]
	v_pk_mul_f32 v[108:109], v[108:109], v[218:219] op_sel_hi:[1,0]
	v_pk_mul_f32 v[120:121], v[120:121], v[124:125]
	v_mul_f32_e32 v124, 0xbfb8aa3b, v122
	v_mul_f32_e32 v125, 0xbfb8aa3b, v123
	v_exp_f32_e32 v124, v124
	v_exp_f32_e32 v125, v125
	v_cvt_pk_bf16_f32 v120, v120, v121
	v_pk_mul_f32 v[110:111], v[110:111], v[218:219] op_sel_hi:[1,0]
	v_add_f32_e32 v124, 1.0, v124
	v_add_f32_e32 v125, 1.0, v125
	v_rcp_f32_e32 v124, v124
	v_rcp_f32_e32 v125, v125
	v_pk_mul_f32 v[104:105], v[104:105], v[218:219] op_sel_hi:[1,0]
	v_pk_mul_f32 v[106:107], v[106:107], v[218:219] op_sel_hi:[1,0]
	v_pk_mul_f32 v[100:101], v[100:101], v[218:219] op_sel_hi:[1,0]
	v_pk_mul_f32 v[122:123], v[122:123], v[124:125]
	v_pk_mul_f32 v[102:103], v[102:103], v[218:219] op_sel_hi:[1,0]
	v_cvt_pk_bf16_f32 v121, v122, v123
	flat_store_dwordx2 v[130:131], v[120:121] offset:32
	v_mul_f32_e32 v120, 0xbfb8aa3b, v116
	v_mul_f32_e32 v121, 0xbfb8aa3b, v117
	v_exp_f32_e32 v120, v120
	v_exp_f32_e32 v121, v121
	v_pk_mul_f32 v[96:97], v[96:97], v[218:219] op_sel_hi:[1,0]
	v_pk_mul_f32 v[98:99], v[98:99], v[218:219] op_sel_hi:[1,0]
	v_add_f32_e32 v120, 1.0, v120
	v_add_f32_e32 v121, 1.0, v121
	v_rcp_f32_e32 v120, v120
	v_rcp_f32_e32 v121, v121
	v_pk_mul_f32 v[92:93], v[92:93], v[216:217] op_sel_hi:[1,0]
	v_pk_mul_f32 v[94:95], v[94:95], v[216:217] op_sel_hi:[1,0]
	v_pk_mul_f32 v[88:89], v[88:89], v[216:217] op_sel_hi:[1,0]
	v_pk_mul_f32 v[116:117], v[116:117], v[120:121]
	v_mul_f32_e32 v120, 0xbfb8aa3b, v118
	v_mul_f32_e32 v121, 0xbfb8aa3b, v119
	v_exp_f32_e32 v120, v120
	v_exp_f32_e32 v121, v121
	v_cvt_pk_bf16_f32 v116, v116, v117
	v_pk_mul_f32 v[90:91], v[90:91], v[216:217] op_sel_hi:[1,0]
	v_add_f32_e32 v120, 1.0, v120
	v_add_f32_e32 v121, 1.0, v121
	v_rcp_f32_e32 v120, v120
	v_rcp_f32_e32 v121, v121
	v_pk_mul_f32 v[84:85], v[84:85], v[216:217] op_sel_hi:[1,0]
	v_pk_mul_f32 v[86:87], v[86:87], v[216:217] op_sel_hi:[1,0]
	v_pk_mul_f32 v[80:81], v[80:81], v[216:217] op_sel_hi:[1,0]
	v_pk_mul_f32 v[118:119], v[118:119], v[120:121]
	v_pk_mul_f32 v[82:83], v[82:83], v[216:217] op_sel_hi:[1,0]
	v_cvt_pk_bf16_f32 v117, v118, v119
	flat_store_dwordx2 v[130:131], v[116:117] offset:64
	v_mul_f32_e32 v116, 0xbfb8aa3b, v112
	v_mul_f32_e32 v117, 0xbfb8aa3b, v113
	v_exp_f32_e32 v116, v116
	v_exp_f32_e32 v117, v117
	v_pk_mul_f32 v[76:77], v[76:77], v[214:215] op_sel_hi:[1,0]
	v_pk_mul_f32 v[78:79], v[78:79], v[214:215] op_sel_hi:[1,0]
	v_add_f32_e32 v116, 1.0, v116
	v_add_f32_e32 v117, 1.0, v117
	v_rcp_f32_e32 v116, v116
	v_rcp_f32_e32 v117, v117
	v_pk_mul_f32 v[72:73], v[72:73], v[214:215] op_sel_hi:[1,0]
	v_pk_mul_f32 v[74:75], v[74:75], v[214:215] op_sel_hi:[1,0]
	v_pk_mul_f32 v[68:69], v[68:69], v[214:215] op_sel_hi:[1,0]
	v_pk_mul_f32 v[112:113], v[112:113], v[116:117]
	v_mul_f32_e32 v116, 0xbfb8aa3b, v114
	v_mul_f32_e32 v117, 0xbfb8aa3b, v115
	v_exp_f32_e32 v116, v116
	v_exp_f32_e32 v117, v117
	v_cvt_pk_bf16_f32 v112, v112, v113
	v_pk_mul_f32 v[70:71], v[70:71], v[214:215] op_sel_hi:[1,0]
	v_add_f32_e32 v116, 1.0, v116
	v_add_f32_e32 v117, 1.0, v117
	v_rcp_f32_e32 v116, v116
	v_rcp_f32_e32 v117, v117
	v_pk_mul_f32 v[64:65], v[64:65], v[214:215] op_sel_hi:[1,0]
	v_pk_mul_f32 v[66:67], v[66:67], v[214:215] op_sel_hi:[1,0]
	v_pk_mul_f32 v[114:115], v[114:115], v[116:117]
	s_nop 0
	v_cvt_pk_bf16_f32 v113, v114, v115
	v_mul_f32_e32 v114, 0xbfb8aa3b, v108
	v_mul_f32_e32 v115, 0xbfb8aa3b, v109
	v_exp_f32_e32 v114, v114
	v_exp_f32_e32 v115, v115
	flat_store_dwordx2 v[130:131], v[112:113] offset:96
	v_lshlrev_b64 v[112:113], 9, v[202:203]
	v_add_f32_e32 v114, 1.0, v114
	v_add_f32_e32 v115, 1.0, v115
	v_rcp_f32_e32 v114, v114
	v_rcp_f32_e32 v115, v115
	v_lshl_add_u64 v[112:113], v[128:129], 0, v[112:113]
	v_pk_mul_f32 v[108:109], v[108:109], v[114:115]
	v_mul_f32_e32 v114, 0xbfb8aa3b, v110
	v_mul_f32_e32 v115, 0xbfb8aa3b, v111
	v_exp_f32_e32 v114, v114
	v_exp_f32_e32 v115, v115
	v_cvt_pk_bf16_f32 v108, v108, v109
	v_add_f32_e32 v114, 1.0, v114
	v_add_f32_e32 v115, 1.0, v115
	v_rcp_f32_e32 v114, v114
	v_rcp_f32_e32 v115, v115
	s_nop 0
	v_pk_mul_f32 v[110:111], v[110:111], v[114:115]
	s_nop 0
	v_cvt_pk_bf16_f32 v109, v110, v111
	flat_store_dwordx2 v[112:113], v[108:109]
	v_mul_f32_e32 v108, 0xbfb8aa3b, v104
	v_mul_f32_e32 v109, 0xbfb8aa3b, v105
	v_exp_f32_e32 v108, v108
	v_exp_f32_e32 v109, v109
	v_add_f32_e32 v108, 1.0, v108
	v_add_f32_e32 v109, 1.0, v109
	v_rcp_f32_e32 v108, v108
	v_rcp_f32_e32 v109, v109
	s_nop 0
	v_pk_mul_f32 v[104:105], v[104:105], v[108:109]
	v_mul_f32_e32 v108, 0xbfb8aa3b, v106
	v_mul_f32_e32 v109, 0xbfb8aa3b, v107
	v_exp_f32_e32 v108, v108
	v_exp_f32_e32 v109, v109
	v_cvt_pk_bf16_f32 v104, v104, v105
	v_add_f32_e32 v108, 1.0, v108
	v_add_f32_e32 v109, 1.0, v109
	v_rcp_f32_e32 v108, v108
	v_rcp_f32_e32 v109, v109
	s_nop 0
	v_pk_mul_f32 v[106:107], v[106:107], v[108:109]
	s_nop 0
	v_cvt_pk_bf16_f32 v105, v106, v107
	flat_store_dwordx2 v[112:113], v[104:105] offset:32
	v_mul_f32_e32 v104, 0xbfb8aa3b, v100
	v_mul_f32_e32 v105, 0xbfb8aa3b, v101
	v_exp_f32_e32 v104, v104
	v_exp_f32_e32 v105, v105
	v_add_f32_e32 v104, 1.0, v104
	v_add_f32_e32 v105, 1.0, v105
	v_rcp_f32_e32 v104, v104
	v_rcp_f32_e32 v105, v105
	s_nop 0
	v_pk_mul_f32 v[100:101], v[100:101], v[104:105]
	v_mul_f32_e32 v104, 0xbfb8aa3b, v102
	v_mul_f32_e32 v105, 0xbfb8aa3b, v103
	v_exp_f32_e32 v104, v104
	v_exp_f32_e32 v105, v105
	v_cvt_pk_bf16_f32 v100, v100, v101
	v_add_f32_e32 v104, 1.0, v104
	v_add_f32_e32 v105, 1.0, v105
	v_rcp_f32_e32 v104, v104
	v_rcp_f32_e32 v105, v105
	s_nop 0
	v_pk_mul_f32 v[102:103], v[102:103], v[104:105]
	s_nop 0
	v_cvt_pk_bf16_f32 v101, v102, v103
	flat_store_dwordx2 v[112:113], v[100:101] offset:64
	v_mul_f32_e32 v100, 0xbfb8aa3b, v96
	v_mul_f32_e32 v101, 0xbfb8aa3b, v97
	v_exp_f32_e32 v100, v100
	v_exp_f32_e32 v101, v101
	v_add_f32_e32 v100, 1.0, v100
	v_add_f32_e32 v101, 1.0, v101
	v_rcp_f32_e32 v100, v100
	v_rcp_f32_e32 v101, v101
	s_nop 0
	v_pk_mul_f32 v[96:97], v[96:97], v[100:101]
	v_mul_f32_e32 v100, 0xbfb8aa3b, v98
	v_mul_f32_e32 v101, 0xbfb8aa3b, v99
	v_exp_f32_e32 v100, v100
	v_exp_f32_e32 v101, v101
	v_cvt_pk_bf16_f32 v96, v96, v97
	v_add_f32_e32 v100, 1.0, v100
	v_add_f32_e32 v101, 1.0, v101
	v_rcp_f32_e32 v100, v100
	v_rcp_f32_e32 v101, v101
	s_nop 0
	v_pk_mul_f32 v[98:99], v[98:99], v[100:101]
	s_nop 0
	v_cvt_pk_bf16_f32 v97, v98, v99
	v_mul_f32_e32 v98, 0xbfb8aa3b, v92
	v_mul_f32_e32 v99, 0xbfb8aa3b, v93
	v_exp_f32_e32 v98, v98
	v_exp_f32_e32 v99, v99
	flat_store_dwordx2 v[112:113], v[96:97] offset:96
	v_lshlrev_b64 v[96:97], 9, v[200:201]
	v_add_f32_e32 v98, 1.0, v98
	v_add_f32_e32 v99, 1.0, v99
	v_rcp_f32_e32 v98, v98
	v_rcp_f32_e32 v99, v99
	v_lshl_add_u64 v[96:97], v[128:129], 0, v[96:97]
	v_pk_mul_f32 v[92:93], v[92:93], v[98:99]
	v_mul_f32_e32 v98, 0xbfb8aa3b, v94
	v_mul_f32_e32 v99, 0xbfb8aa3b, v95
	v_exp_f32_e32 v98, v98
	v_exp_f32_e32 v99, v99
	v_cvt_pk_bf16_f32 v92, v92, v93
	v_add_f32_e32 v98, 1.0, v98
	v_add_f32_e32 v99, 1.0, v99
	v_rcp_f32_e32 v98, v98
	v_rcp_f32_e32 v99, v99
	s_nop 0
	v_pk_mul_f32 v[94:95], v[94:95], v[98:99]
	s_nop 0
	v_cvt_pk_bf16_f32 v93, v94, v95
	flat_store_dwordx2 v[96:97], v[92:93]
	v_mul_f32_e32 v92, 0xbfb8aa3b, v88
	v_mul_f32_e32 v93, 0xbfb8aa3b, v89
	v_exp_f32_e32 v92, v92
	v_exp_f32_e32 v93, v93
	v_add_f32_e32 v92, 1.0, v92
	v_add_f32_e32 v93, 1.0, v93
	v_rcp_f32_e32 v92, v92
	v_rcp_f32_e32 v93, v93
	s_nop 0
	v_pk_mul_f32 v[88:89], v[88:89], v[92:93]
	v_mul_f32_e32 v92, 0xbfb8aa3b, v90
	v_mul_f32_e32 v93, 0xbfb8aa3b, v91
	v_exp_f32_e32 v92, v92
	v_exp_f32_e32 v93, v93
	v_cvt_pk_bf16_f32 v88, v88, v89
	v_add_f32_e32 v92, 1.0, v92
	v_add_f32_e32 v93, 1.0, v93
	v_rcp_f32_e32 v92, v92
	v_rcp_f32_e32 v93, v93
	s_nop 0
	v_pk_mul_f32 v[90:91], v[90:91], v[92:93]
	s_nop 0
	v_cvt_pk_bf16_f32 v89, v90, v91
	flat_store_dwordx2 v[96:97], v[88:89] offset:32
	v_mul_f32_e32 v88, 0xbfb8aa3b, v84
	v_mul_f32_e32 v89, 0xbfb8aa3b, v85
	v_exp_f32_e32 v88, v88
	v_exp_f32_e32 v89, v89
	v_add_f32_e32 v88, 1.0, v88
	v_add_f32_e32 v89, 1.0, v89
	v_rcp_f32_e32 v88, v88
	v_rcp_f32_e32 v89, v89
	s_nop 0
	v_pk_mul_f32 v[84:85], v[84:85], v[88:89]
	v_mul_f32_e32 v88, 0xbfb8aa3b, v86
	v_mul_f32_e32 v89, 0xbfb8aa3b, v87
	v_exp_f32_e32 v88, v88
	v_exp_f32_e32 v89, v89
	v_cvt_pk_bf16_f32 v84, v84, v85
	v_add_f32_e32 v88, 1.0, v88
	v_add_f32_e32 v89, 1.0, v89
	v_rcp_f32_e32 v88, v88
	v_rcp_f32_e32 v89, v89
	s_nop 0
	v_pk_mul_f32 v[86:87], v[86:87], v[88:89]
	s_nop 0
	v_cvt_pk_bf16_f32 v85, v86, v87
	flat_store_dwordx2 v[96:97], v[84:85] offset:64
	v_mul_f32_e32 v84, 0xbfb8aa3b, v80
	v_mul_f32_e32 v85, 0xbfb8aa3b, v81
	v_exp_f32_e32 v84, v84
	v_exp_f32_e32 v85, v85
	v_add_f32_e32 v84, 1.0, v84
	v_add_f32_e32 v85, 1.0, v85
	v_rcp_f32_e32 v84, v84
	v_rcp_f32_e32 v85, v85
	s_nop 0
	v_pk_mul_f32 v[80:81], v[80:81], v[84:85]
	v_mul_f32_e32 v84, 0xbfb8aa3b, v82
	v_mul_f32_e32 v85, 0xbfb8aa3b, v83
	v_exp_f32_e32 v84, v84
	v_exp_f32_e32 v85, v85
	v_cvt_pk_bf16_f32 v80, v80, v81
	v_add_f32_e32 v84, 1.0, v84
	v_add_f32_e32 v85, 1.0, v85
	v_rcp_f32_e32 v84, v84
	v_rcp_f32_e32 v85, v85
	s_nop 0
	v_pk_mul_f32 v[82:83], v[82:83], v[84:85]
	s_nop 0
	v_cvt_pk_bf16_f32 v81, v82, v83
	v_mul_f32_e32 v82, 0xbfb8aa3b, v76
	v_mul_f32_e32 v83, 0xbfb8aa3b, v77
	v_exp_f32_e32 v82, v82
	v_exp_f32_e32 v83, v83
	flat_store_dwordx2 v[96:97], v[80:81] offset:96
	v_lshlrev_b64 v[80:81], 9, v[198:199]
	v_add_f32_e32 v82, 1.0, v82
	v_add_f32_e32 v83, 1.0, v83
	v_rcp_f32_e32 v82, v82
	v_rcp_f32_e32 v83, v83
	v_lshl_add_u64 v[80:81], v[128:129], 0, v[80:81]
	v_pk_mul_f32 v[76:77], v[76:77], v[82:83]
	v_mul_f32_e32 v82, 0xbfb8aa3b, v78
	v_mul_f32_e32 v83, 0xbfb8aa3b, v79
	v_exp_f32_e32 v82, v82
	v_exp_f32_e32 v83, v83
	v_cvt_pk_bf16_f32 v76, v76, v77
	v_add_f32_e32 v82, 1.0, v82
	v_add_f32_e32 v83, 1.0, v83
	v_rcp_f32_e32 v82, v82
	v_rcp_f32_e32 v83, v83
	s_nop 0
	v_pk_mul_f32 v[78:79], v[78:79], v[82:83]
	s_nop 0
	v_cvt_pk_bf16_f32 v77, v78, v79
	flat_store_dwordx2 v[80:81], v[76:77]
	v_mul_f32_e32 v76, 0xbfb8aa3b, v72
	v_mul_f32_e32 v77, 0xbfb8aa3b, v73
	v_exp_f32_e32 v76, v76
	v_exp_f32_e32 v77, v77
	v_add_f32_e32 v76, 1.0, v76
	v_add_f32_e32 v77, 1.0, v77
	v_rcp_f32_e32 v76, v76
	v_rcp_f32_e32 v77, v77
	s_nop 0
	v_pk_mul_f32 v[72:73], v[72:73], v[76:77]
	v_mul_f32_e32 v76, 0xbfb8aa3b, v74
	v_mul_f32_e32 v77, 0xbfb8aa3b, v75
	v_exp_f32_e32 v76, v76
	v_exp_f32_e32 v77, v77
	v_cvt_pk_bf16_f32 v72, v72, v73
	v_add_f32_e32 v76, 1.0, v76
	v_add_f32_e32 v77, 1.0, v77
	v_rcp_f32_e32 v76, v76
	v_rcp_f32_e32 v77, v77
	s_nop 0
	v_pk_mul_f32 v[74:75], v[74:75], v[76:77]
	s_nop 0
	v_cvt_pk_bf16_f32 v73, v74, v75
	flat_store_dwordx2 v[80:81], v[72:73] offset:32
	v_mul_f32_e32 v72, 0xbfb8aa3b, v68
	v_mul_f32_e32 v73, 0xbfb8aa3b, v69
	v_exp_f32_e32 v72, v72
	v_exp_f32_e32 v73, v73
	v_add_f32_e32 v72, 1.0, v72
	v_add_f32_e32 v73, 1.0, v73
	v_rcp_f32_e32 v72, v72
	v_rcp_f32_e32 v73, v73
	s_nop 0
	v_pk_mul_f32 v[68:69], v[68:69], v[72:73]
	v_mul_f32_e32 v72, 0xbfb8aa3b, v70
	v_mul_f32_e32 v73, 0xbfb8aa3b, v71
	v_exp_f32_e32 v72, v72
	v_exp_f32_e32 v73, v73
	v_cvt_pk_bf16_f32 v68, v68, v69
	v_add_f32_e32 v72, 1.0, v72
	v_add_f32_e32 v73, 1.0, v73
	v_rcp_f32_e32 v72, v72
	v_rcp_f32_e32 v73, v73
	s_nop 0
	v_pk_mul_f32 v[70:71], v[70:71], v[72:73]
	s_nop 0
	v_cvt_pk_bf16_f32 v69, v70, v71
	flat_store_dwordx2 v[80:81], v[68:69] offset:64
	v_mul_f32_e32 v68, 0xbfb8aa3b, v64
	v_mul_f32_e32 v69, 0xbfb8aa3b, v65
	v_exp_f32_e32 v68, v68
	v_exp_f32_e32 v69, v69
	v_add_f32_e32 v68, 1.0, v68
	v_add_f32_e32 v69, 1.0, v69
	v_rcp_f32_e32 v68, v68
	v_rcp_f32_e32 v69, v69
	s_nop 0
	v_pk_mul_f32 v[64:65], v[64:65], v[68:69]
	v_mul_f32_e32 v68, 0xbfb8aa3b, v66
	v_mul_f32_e32 v69, 0xbfb8aa3b, v67
	v_exp_f32_e32 v68, v68
	v_exp_f32_e32 v69, v69
	v_cvt_pk_bf16_f32 v64, v64, v65
	v_add_f32_e32 v68, 1.0, v68
	v_add_f32_e32 v69, 1.0, v69
	v_rcp_f32_e32 v68, v68
	v_rcp_f32_e32 v69, v69
	s_nop 0
	v_pk_mul_f32 v[66:67], v[66:67], v[68:69]
	s_nop 0
	v_cvt_pk_bf16_f32 v65, v66, v67
	flat_store_dwordx2 v[80:81], v[64:65] offset:96
